# v33 + sc1 (write-through) on P0's XN row stores to leave no dirty lines for the first grid barrier's write-back
# speedup vs baseline: 1.0126x; 1.0126x over previous
; __device__ __forceinline__ unsigned f2bf(float f) { return pk2(f, 0.f) & 0xffffu; }
; __device__ __forceinline__ void rms9_finish(f32x4 (&v)[9][4], bool xe, const float* gain, bf16* o0, bf16* oe, int lane) {
;     ...
;     for (int r = 0; r < 9; ++r) { s[r] = 0.f;
; #pragma unroll
;         for (int j = 0; j < 4; ++j) s[r] += (v[r][j].x * v[r][j].x + v[r][j].y * v[r][j].y) + (v[r][j].z * v[r][j].z + v[r][j].w * v[r][j].w); }
; __device__ __forceinline__ void s5_tables_item(Frame& F, int item, const S5TabRegs& R) {
;     ...
; #pragma unroll
;     for (int i = 0; i < 4; ++i) { const int idx = tid + 512 * i, np = 16 * part + (idx >> 7), k = idx & 127, s = k >> 4, cp = k & 15, n = np & 63;
;         const float pr = Pre[(7 - s) * 64 + n], pi = Pim[(7 - s) * 64 + n], br = Bre[n * 16 + cp], bi = Bim[n * 16 + cp];
;         WG[np * 128 + k] = (bf16)f2bf(np < 64 ? pr * br - pi * bi : pr * bi + pi * br); }
; #pragma unroll
;     for (int i = 0; i < 4; ++i) { const int idx = tid + 512 * i, col = 16 * part + (idx >> 7), np = idx & 127, t = col >> 4, c = col & 15, n = np & 63;
;         const float pr = Pre[(t + 1) * 64 + n], pi = Pim[(t + 1) * 64 + n], cr = Cre[c * 64 + n], ci = Cim[c * 64 + n];
;         VG[col * 128 + np] = (bf16)f2bf(np < 64 ? cr * pr - ci * pi : -(cr * pi + ci * pr)); }
;     asm volatile("s_waitcnt lgkmcnt(0)" ::: "memory"); __builtin_amdgcn_s_barrier(); asm volatile("" ::: "memory");
.LBB0_32:
	s_or_b64 exec, exec, s[10:11]
	s_add_u32 s8, s4, 0x8000
	s_addc_u32 s9, s5, 0
	s_lshl_b32 s10, s15, 4
	v_lshrrev_b32_e32 v156, 7, v0
	v_lshrrev_b32_e32 v148, 7, v148
	v_lshlrev_b32_e32 v153, 2, v0
	v_bitop3_b32 v158, v156, 51, s10 bitop3:0xc8
	s_movk_i32 s11, 0x1c0
	v_bitop3_b32 v162, v148, 55, s10 bitop3:0xc8
	v_bitop3_b32 v159, v158, s11, v153 bitop3:0x34
	v_bitop3_b32 v163, v162, s11, v153 bitop3:0x34
	v_lshlrev_b32_e32 v159, 2, v159
	s_add_i32 s22, 0, 0x10000
	s_add_i32 s23, 0, 0x10900
	v_lshl_or_b32 v158, v158, 6, v147
	s_add_i32 s24, 0, 0x13400
	s_add_i32 s25, 0, 0x14400
	v_lshlrev_b32_e32 v163, 2, v163
	v_lshl_or_b32 v162, v162, 6, v147
	v_add_u32_e32 v160, s22, v159
	v_add_u32_e32 v159, s23, v159
	v_add_u32_e32 v161, s24, v158
	v_add_u32_e32 v158, s25, v158
	v_add_u32_e32 v164, s22, v163
	v_add_u32_e32 v163, s23, v163
	v_add_u32_e32 v165, s24, v162
	v_add_u32_e32 v162, s25, v162
	ds_read_b32 v160, v160
	ds_read_b32 v159, v159
	ds_read_b32 v161, v161
	ds_read_b32 v158, v158
	ds_read_b32 v164, v164
	ds_read_b32 v163, v163
	ds_read_b32 v165, v165
	ds_read_b32 v162, v162
	s_cmp_lt_u32 s15, 4
	s_waitcnt lgkmcnt(4)
	v_mul_f32_e32 v166, v159, v158
	v_mul_f32_e32 v158, v160, v158
	v_and_b32_e32 v149, 0x7f, v0
	v_fma_f32 v166, v160, v161, -v166
	v_fmac_f32_e32 v158, v159, v161
	s_cselect_b64 vcc, -1, 0
	v_or_b32_e32 v157, s10, v156
	v_cndmask_b32_e32 v158, v158, v166, vcc
	v_lshlrev_b32_e32 v159, 1, v149
	s_waitcnt lgkmcnt(0)
	v_mul_f32_e32 v160, v163, v162
	v_mul_f32_e32 v161, v164, v162
	v_cvt_pk_bf16_f32 v158, v158, s0
	v_lshl_or_b32 v157, v157, 8, v159
	v_fma_f32 v160, v164, v165, -v160
	v_fmac_f32_e32 v161, v163, v165
	global_store_short v157, v158, s[4:5]
	v_or_b32_e32 v158, s10, v148
	v_cndmask_b32_e32 v160, v161, v160, vcc
	v_cvt_pk_bf16_f32 v160, v160, s0
	v_lshl_or_b32 v158, v158, 8, v159
	v_or_b32_e32 v166, 0x600, v0
	global_store_short v158, v160, s[4:5]
	v_or_b32_e32 v160, 8, v156
	v_lshrrev_b32_e32 v167, 7, v166
	v_bitop3_b32 v162, v160, 59, s10 bitop3:0xc8
	v_bitop3_b32 v168, v167, 63, s10 bitop3:0xc8
	v_bitop3_b32 v163, v162, s11, v153 bitop3:0x34
	v_bitop3_b32 v153, v168, s11, v153 bitop3:0x34
	v_lshlrev_b32_e32 v163, 2, v163
	v_lshl_or_b32 v162, v162, 6, v147
	v_lshlrev_b32_e32 v153, 2, v153
	v_lshl_or_b32 v147, v168, 6, v147
	v_add_u32_e32 v164, s22, v163
	v_add_u32_e32 v163, s23, v163
	v_add_u32_e32 v165, s24, v162
	v_add_u32_e32 v162, s25, v162
	v_add_u32_e32 v169, s22, v153
	v_add_u32_e32 v153, s23, v153
	v_add_u32_e32 v168, s24, v147
	v_add_u32_e32 v147, s25, v147
	ds_read_b32 v164, v164
	ds_read_b32 v163, v163
	ds_read_b32 v165, v165
	ds_read_b32 v162, v162
	ds_read_b32 v169, v169
	ds_read_b32 v153, v153
	ds_read_b32 v168, v168
	ds_read_b32 v147, v147
	s_waitcnt lgkmcnt(4)
	v_mul_f32_e32 v170, v163, v162
	v_mul_f32_e32 v162, v164, v162
	v_fma_f32 v170, v164, v165, -v170
	v_fmac_f32_e32 v162, v163, v165
	v_or_b32_e32 v161, s10, v160
	v_cndmask_b32_e32 v162, v162, v170, vcc
	v_cvt_pk_bf16_f32 v162, v162, s0
	v_lshl_or_b32 v161, v161, 8, v159
	global_store_short v161, v162, s[4:5]
	v_or_b32_e32 v162, s10, v167
	s_waitcnt lgkmcnt(0)
	v_mul_f32_e32 v163, v153, v147
	v_mul_f32_e32 v147, v169, v147
	v_fma_f32 v163, v169, v168, -v163
	v_fmac_f32_e32 v147, v153, v168
	v_cmp_gt_u32_e32 vcc, 64, v162
	v_lshl_or_b32 v153, v162, 8, v159
	v_lshl_or_b32 v156, v156, 8, v146
	v_cndmask_b32_e32 v147, v147, v163, vcc
	v_cvt_pk_bf16_f32 v147, v147, s0
	global_store_short v153, v147, s[4:5]
	s_lshl_b32 s4, s15, 6
	v_add_lshl_u32 v147, s4, v150, 2
	s_add_i32 s4, 0, 0x11400
	s_add_i32 s5, 0, 0x12400
	v_lshl_or_b32 v148, v148, 8, v146
	v_lshl_or_b32 v146, v160, 8, v146
	v_add_u32_e32 v159, s22, v147
	v_add_u32_e32 v147, s23, v147
	v_add_u32_e32 v162, s4, v156
	v_add_u32_e32 v156, s5, v156
	v_add_u32_e32 v163, s4, v148
	v_add_u32_e32 v148, s5, v148
	v_add_u32_e32 v160, s4, v146
	v_add_u32_e32 v146, s5, v146
	ds_read_b32 v159, v159
	ds_read_b32 v147, v147
	ds_read_b32 v162, v162
	ds_read_b32 v156, v156
	ds_read_b32 v163, v163
	ds_read_b32 v148, v148
	ds_read_b32 v160, v160
	ds_read_b32 v146, v146
	s_waitcnt lgkmcnt(4)
	v_mul_f32_e32 v164, v147, v156
	v_mul_f32_e32 v156, v159, v156
	v_fma_f32 v164, v159, v162, -v164
	v_fmac_f32_e32 v156, v147, v162
	v_cmp_gt_u32_e32 vcc, 64, v149
	s_movk_i32 s10, 0x3c0
	s_load_dwordx16 s[56:71], s[0:1], 0x0
	v_cndmask_b32_e64 v149, -v156, v164, vcc
	v_cvt_pk_bf16_f32 v149, v149, s0
	global_store_short v157, v149, s[8:9]
	s_waitcnt lgkmcnt(0)
	v_mul_f32_e32 v149, v147, v148
	v_mul_f32_e32 v148, v159, v148
	v_fma_f32 v149, v159, v163, -v149
	v_fmac_f32_e32 v148, v147, v163
	v_cndmask_b32_e64 v148, -v148, v149, vcc
	v_lshrrev_b32_e32 v149, 1, v166
	v_and_or_b32 v149, v149, s10, v154
	v_cvt_pk_bf16_f32 v148, v148, s0
	v_lshlrev_b32_e32 v149, 2, v149
	global_store_short v158, v148, s[8:9]
	v_add_u32_e32 v156, s4, v149
	v_add_u32_e32 v149, s5, v149
	ds_read_b32 v156, v156
	ds_read_b32 v149, v149
	v_mul_f32_e32 v148, v147, v146
	v_mul_f32_e32 v146, v159, v146
	v_fma_f32 v148, v159, v160, -v148
	v_fmac_f32_e32 v146, v147, v160
	v_cndmask_b32_e64 v146, -v146, v148, vcc
	v_cvt_pk_bf16_f32 v146, v146, s0
	global_store_short v161, v146, s[8:9]
	s_waitcnt lgkmcnt(0)
	v_mul_f32_e32 v146, v147, v149
	v_mul_f32_e32 v148, v159, v149
	v_fma_f32 v146, v159, v156, -v146
	v_fmac_f32_e32 v148, v147, v156
	v_cndmask_b32_e64 v146, -v148, v146, vcc
	v_cvt_pk_bf16_f32 v146, v146, s0
	global_store_short v153, v146, s[8:9]
	v_pk_mul_f32 v[146:147], v[144:145], v[144:145]
	v_pk_mul_f32 v[148:149], v[142:143], v[142:143]
	v_mul_f32_e32 v153, v38, v38
	v_pk_mov_b32 v[156:157], v[148:149], v[146:147] op_sel:[1,0]
	v_mov_b32_e32 v149, v147
	v_pk_add_f32 v[146:147], v[156:157], v[148:149]
	v_pk_mul_f32 v[148:149], v[108:109], v[108:109]
	v_pk_mul_f32 v[156:157], v[106:107], v[106:107]
	v_pk_add_f32 v[146:147], v[146:147], v[146:147] op_sel:[0,1] op_sel_hi:[1,0]
	v_pk_mov_b32 v[158:159], v[156:157], v[148:149] op_sel:[1,0]
	v_mov_b32_e32 v157, v149
	v_pk_add_f32 v[148:149], v[158:159], v[156:157]
	v_mul_f32_e32 v156, v39, v39
	v_pk_add_f32 v[148:149], v[148:149], v[148:149] op_sel:[0,1] op_sel_hi:[1,0]
	v_mov_b32_e32 v147, v153
	v_mov_b32_e32 v149, v156
	v_pk_add_f32 v[146:147], v[146:147], v[148:149]
	v_mul_f32_e32 v148, v71, v71
	v_mul_f32_e32 v157, v40, v40
	v_pk_fma_f32 v[148:149], v[70:71], v[70:71], v[148:149] op_sel_hi:[1,1,0]
	v_mul_f32_e32 v156, v73, v73
	v_mul_f32_e32 v158, v41, v41
	v_mov_b32_e32 v149, v157
	v_pk_fma_f32 v[156:157], v[72:73], v[72:73], v[156:157] op_sel_hi:[1,1,0]
	s_waitcnt lgkmcnt(0)
	s_barrier
; __device__ __forceinline__ void rms9_finish(f32x4 (&v)[9][4], bool xe, const float* gain, bf16* o0, bf16* oe, int lane) {
;     ...
;     for (int r = 0; r < 9; ++r) { s[r] = 0.f;
; #pragma unroll
;         for (int j = 0; j < 4; ++j) s[r] += (v[r][j].x * v[r][j].x + v[r][j].y * v[r][j].y) + (v[r][j].z * v[r][j].z + v[r][j].w * v[r][j].w); }
	v_mov_b32_e32 v157, v158
	v_pk_add_f32 v[148:149], v[148:149], v[156:157]
	s_lshl_b64 s[4:5], s[6:7], 1
	v_pk_add_f32 v[146:147], v[146:147], v[148:149]
	v_pk_mul_f32 v[148:149], v[138:139], v[138:139]
	v_add_f32_e32 v153, v146, v147
	v_pk_mul_f32 v[146:147], v[140:141], v[140:141]
	s_add_u32 s6, s46, s4
	v_pk_mov_b32 v[156:157], v[148:149], v[146:147] op_sel:[1,0]
	v_mov_b32_e32 v149, v147
	v_pk_add_f32 v[146:147], v[156:157], v[148:149]
	v_pk_mul_f32 v[148:149], v[92:93], v[92:93]
	v_pk_mul_f32 v[156:157], v[90:91], v[90:91]
	v_pk_add_f32 v[146:147], v[146:147], v[146:147] op_sel:[0,1] op_sel_hi:[1,0]
	v_pk_mov_b32 v[158:159], v[156:157], v[148:149] op_sel:[1,0]
	v_mov_b32_e32 v157, v149
	v_pk_add_f32 v[148:149], v[158:159], v[156:157]
	v_mul_f32_e32 v156, v34, v34
	v_mul_f32_e32 v157, v35, v35
	v_pk_add_f32 v[148:149], v[148:149], v[148:149] op_sel:[0,1] op_sel_hi:[1,0]
	v_mov_b32_e32 v147, v156
	v_mov_b32_e32 v149, v157
	v_pk_add_f32 v[146:147], v[146:147], v[148:149]
	v_mul_f32_e32 v148, v67, v67
	v_mul_f32_e32 v156, v69, v69
	v_mul_f32_e32 v158, v36, v36
	v_mul_f32_e32 v159, v37, v37
	v_pk_fma_f32 v[148:149], v[66:67], v[66:67], v[148:149] op_sel_hi:[1,1,0]
	v_pk_fma_f32 v[156:157], v[68:69], v[68:69], v[156:157] op_sel_hi:[1,1,0]
	v_mov_b32_e32 v149, v158
	v_mov_b32_e32 v157, v159
	v_pk_add_f32 v[148:149], v[148:149], v[156:157]
	s_addc_u32 s7, s47, s5
	v_pk_add_f32 v[146:147], v[146:147], v[148:149]
	v_pk_mul_f32 v[148:149], v[134:135], v[134:135]
	v_add_f32_e32 v160, v146, v147
	v_pk_mul_f32 v[146:147], v[136:137], v[136:137]
	s_lshl_b64 s[4:5], s[34:35], 11
	v_pk_mov_b32 v[156:157], v[148:149], v[146:147] op_sel:[1,0]
	v_mov_b32_e32 v149, v147
	v_pk_add_f32 v[146:147], v[156:157], v[148:149]
	v_pk_mul_f32 v[148:149], v[84:85], v[84:85]
	v_pk_mul_f32 v[156:157], v[82:83], v[82:83]
	v_pk_add_f32 v[146:147], v[146:147], v[146:147] op_sel:[0,1] op_sel_hi:[1,0]
	v_pk_mov_b32 v[158:159], v[156:157], v[148:149] op_sel:[1,0]
	v_mov_b32_e32 v157, v149
	v_pk_add_f32 v[148:149], v[158:159], v[156:157]
	v_mul_f32_e32 v156, v30, v30
	v_mul_f32_e32 v157, v31, v31
	v_pk_add_f32 v[148:149], v[148:149], v[148:149] op_sel:[0,1] op_sel_hi:[1,0]
	v_mov_b32_e32 v147, v156
	v_mov_b32_e32 v149, v157
	v_pk_add_f32 v[146:147], v[146:147], v[148:149]
	v_mul_f32_e32 v148, v63, v63
	v_mul_f32_e32 v156, v65, v65
	v_mul_f32_e32 v158, v32, v32
	v_mul_f32_e32 v159, v33, v33
	v_pk_fma_f32 v[148:149], v[62:63], v[62:63], v[148:149] op_sel_hi:[1,1,0]
	v_pk_fma_f32 v[156:157], v[64:65], v[64:65], v[156:157] op_sel_hi:[1,1,0]
	v_mov_b32_e32 v149, v158
	v_mov_b32_e32 v157, v159
	v_pk_add_f32 v[148:149], v[148:149], v[156:157]
	s_add_u32 s4, s46, s4
	v_pk_add_f32 v[146:147], v[146:147], v[148:149]
	v_pk_mul_f32 v[148:149], v[130:131], v[130:131]
	v_add_f32_e32 v161, v146, v147
	v_pk_mul_f32 v[146:147], v[132:133], v[132:133]
	s_addc_u32 s5, s47, s5
	v_pk_mov_b32 v[156:157], v[148:149], v[146:147] op_sel:[1,0]
	v_mov_b32_e32 v149, v147
	v_pk_add_f32 v[146:147], v[156:157], v[148:149]
	v_pk_mul_f32 v[148:149], v[88:89], v[88:89]
	v_pk_mul_f32 v[156:157], v[86:87], v[86:87]
	v_pk_add_f32 v[146:147], v[146:147], v[146:147] op_sel:[0,1] op_sel_hi:[1,0]
	v_pk_mov_b32 v[158:159], v[156:157], v[148:149] op_sel:[1,0]
	v_mov_b32_e32 v157, v149
	v_pk_add_f32 v[148:149], v[158:159], v[156:157]
	v_mul_f32_e32 v156, v26, v26
	v_mul_f32_e32 v157, v27, v27
	v_pk_add_f32 v[148:149], v[148:149], v[148:149] op_sel:[0,1] op_sel_hi:[1,0]
	v_mov_b32_e32 v147, v156
	v_mov_b32_e32 v149, v157
	v_pk_add_f32 v[146:147], v[146:147], v[148:149]
	v_mul_f32_e32 v148, v59, v59
	v_mul_f32_e32 v156, v61, v61
	v_mul_f32_e32 v158, v28, v28
	v_mul_f32_e32 v159, v29, v29
	v_pk_fma_f32 v[148:149], v[58:59], v[58:59], v[148:149] op_sel_hi:[1,1,0]
	v_pk_fma_f32 v[156:157], v[60:61], v[60:61], v[156:157] op_sel_hi:[1,1,0]
	v_mov_b32_e32 v149, v158
	v_mov_b32_e32 v157, v159
	v_pk_add_f32 v[148:149], v[148:149], v[156:157]
	s_add_u32 s4, s4, 0x2000000
	v_pk_add_f32 v[146:147], v[146:147], v[148:149]
	v_pk_mul_f32 v[148:149], v[126:127], v[126:127]
	v_add_f32_e32 v162, v146, v147
	v_pk_mul_f32 v[146:147], v[128:129], v[128:129]
	s_addc_u32 s5, s5, 0
	v_pk_mov_b32 v[156:157], v[148:149], v[146:147] op_sel:[1,0]
	v_mov_b32_e32 v149, v147
	v_pk_add_f32 v[146:147], v[156:157], v[148:149]
	v_pk_mul_f32 v[148:149], v[80:81], v[80:81]
	v_pk_mul_f32 v[156:157], v[78:79], v[78:79]
	v_pk_add_f32 v[146:147], v[146:147], v[146:147] op_sel:[0,1] op_sel_hi:[1,0]
	v_pk_mov_b32 v[158:159], v[156:157], v[148:149] op_sel:[1,0]
	v_mov_b32_e32 v157, v149
	v_pk_add_f32 v[148:149], v[158:159], v[156:157]
	v_mul_f32_e32 v156, v22, v22
	v_mul_f32_e32 v157, v23, v23
	v_pk_add_f32 v[148:149], v[148:149], v[148:149] op_sel:[0,1] op_sel_hi:[1,0]
	v_mov_b32_e32 v147, v156
	v_mov_b32_e32 v149, v157
	v_pk_add_f32 v[146:147], v[146:147], v[148:149]
	v_mul_f32_e32 v148, v55, v55
	v_mul_f32_e32 v156, v57, v57
	v_mul_f32_e32 v158, v24, v24
	v_mul_f32_e32 v159, v25, v25
	v_pk_fma_f32 v[148:149], v[54:55], v[54:55], v[148:149] op_sel_hi:[1,1,0]
	v_pk_fma_f32 v[156:157], v[56:57], v[56:57], v[156:157] op_sel_hi:[1,1,0]
	v_mov_b32_e32 v149, v158
	v_mov_b32_e32 v157, v159
	v_pk_add_f32 v[148:149], v[148:149], v[156:157]
	s_add_u32 s8, s6, 0x1000
	v_pk_add_f32 v[146:147], v[146:147], v[148:149]
	v_pk_mul_f32 v[148:149], v[122:123], v[122:123]
	v_add_f32_e32 v163, v146, v147
	v_pk_mul_f32 v[146:147], v[124:125], v[124:125]
	s_addc_u32 s9, s7, 0
	v_pk_mov_b32 v[156:157], v[148:149], v[146:147] op_sel:[1,0]
	v_mov_b32_e32 v149, v147
	v_pk_add_f32 v[146:147], v[156:157], v[148:149]
	v_pk_mul_f32 v[148:149], v[104:105], v[104:105]
; __device__ __forceinline__ void rms9_finish(f32x4 (&v)[9][4], bool xe, const float* gain, bf16* o0, bf16* oe, int lane) {
;     ...
;     for (int r = 0; r < 9; ++r) { s[r] = 0.f;
; #pragma unroll
;         for (int j = 0; j < 4; ++j) s[r] += (v[r][j].x * v[r][j].x + v[r][j].y * v[r][j].y) + (v[r][j].z * v[r][j].z + v[r][j].w * v[r][j].w); }
; #pragma unroll
;     for (int o = 1; o < 64; o <<= 1) {
; #pragma unroll
;         for (int r = 0; r < 9; ++r) s[r] += __shfl_xor(s[r], o); }
	v_pk_mul_f32 v[156:157], v[102:103], v[102:103]
	v_pk_add_f32 v[146:147], v[146:147], v[146:147] op_sel:[0,1] op_sel_hi:[1,0]
	v_pk_mov_b32 v[158:159], v[156:157], v[148:149] op_sel:[1,0]
	v_mov_b32_e32 v157, v149
	v_pk_add_f32 v[148:149], v[158:159], v[156:157]
	v_mul_f32_e32 v156, v18, v18
	v_mul_f32_e32 v157, v19, v19
	v_pk_add_f32 v[148:149], v[148:149], v[148:149] op_sel:[0,1] op_sel_hi:[1,0]
	v_mov_b32_e32 v147, v156
	v_mov_b32_e32 v149, v157
	v_pk_add_f32 v[146:147], v[146:147], v[148:149]
	v_mul_f32_e32 v148, v51, v51
	v_mul_f32_e32 v156, v53, v53
	v_mul_f32_e32 v158, v20, v20
	v_mul_f32_e32 v159, v21, v21
	v_pk_fma_f32 v[148:149], v[50:51], v[50:51], v[148:149] op_sel_hi:[1,1,0]
	v_pk_fma_f32 v[156:157], v[52:53], v[52:53], v[156:157] op_sel_hi:[1,1,0]
	v_mov_b32_e32 v149, v158
	v_mov_b32_e32 v157, v159
	v_pk_add_f32 v[148:149], v[148:149], v[156:157]
	s_add_u32 s10, s6, 0x1800
	v_pk_add_f32 v[146:147], v[146:147], v[148:149]
	v_pk_mul_f32 v[148:149], v[118:119], v[118:119]
	v_add_f32_e32 v164, v146, v147
	v_pk_mul_f32 v[146:147], v[120:121], v[120:121]
	s_addc_u32 s11, s7, 0
	v_pk_mov_b32 v[156:157], v[148:149], v[146:147] op_sel:[1,0]
	v_mov_b32_e32 v149, v147
	v_pk_add_f32 v[146:147], v[156:157], v[148:149]
	v_pk_mul_f32 v[148:149], v[100:101], v[100:101]
	v_pk_mul_f32 v[156:157], v[98:99], v[98:99]
	v_pk_add_f32 v[146:147], v[146:147], v[146:147] op_sel:[0,1] op_sel_hi:[1,0]
	v_pk_mov_b32 v[158:159], v[156:157], v[148:149] op_sel:[1,0]
	v_mov_b32_e32 v157, v149
	v_pk_add_f32 v[148:149], v[158:159], v[156:157]
	v_mul_f32_e32 v156, v14, v14
	v_mul_f32_e32 v157, v15, v15
	v_pk_add_f32 v[148:149], v[148:149], v[148:149] op_sel:[0,1] op_sel_hi:[1,0]
	v_mov_b32_e32 v147, v156
	v_mov_b32_e32 v149, v157
	v_pk_add_f32 v[146:147], v[146:147], v[148:149]
	v_mul_f32_e32 v148, v47, v47
	v_mul_f32_e32 v156, v49, v49
	v_mul_f32_e32 v158, v16, v16
	v_mul_f32_e32 v159, v17, v17
	v_pk_fma_f32 v[148:149], v[46:47], v[46:47], v[148:149] op_sel_hi:[1,1,0]
	v_pk_fma_f32 v[156:157], v[48:49], v[48:49], v[156:157] op_sel_hi:[1,1,0]
	v_mov_b32_e32 v149, v158
	v_mov_b32_e32 v157, v159
	v_pk_add_f32 v[148:149], v[148:149], v[156:157]
	s_add_u32 s22, s6, 0x2000
	v_pk_add_f32 v[146:147], v[146:147], v[148:149]
	v_pk_mul_f32 v[148:149], v[114:115], v[114:115]
	v_add_f32_e32 v165, v146, v147
	v_pk_mul_f32 v[146:147], v[116:117], v[116:117]
	s_addc_u32 s23, s7, 0
	v_pk_mov_b32 v[156:157], v[148:149], v[146:147] op_sel:[1,0]
	v_mov_b32_e32 v149, v147
	v_pk_add_f32 v[146:147], v[156:157], v[148:149]
	v_pk_mul_f32 v[148:149], v[96:97], v[96:97]
	v_pk_mul_f32 v[156:157], v[94:95], v[94:95]
	v_pk_add_f32 v[146:147], v[146:147], v[146:147] op_sel:[0,1] op_sel_hi:[1,0]
	v_pk_mov_b32 v[158:159], v[156:157], v[148:149] op_sel:[1,0]
	v_mov_b32_e32 v157, v149
	v_pk_add_f32 v[148:149], v[158:159], v[156:157]
	v_mul_f32_e32 v156, v6, v6
	v_mul_f32_e32 v157, v7, v7
	v_pk_add_f32 v[148:149], v[148:149], v[148:149] op_sel:[0,1] op_sel_hi:[1,0]
	v_mov_b32_e32 v147, v156
	v_mov_b32_e32 v149, v157
	v_pk_add_f32 v[146:147], v[146:147], v[148:149]
	v_mul_f32_e32 v148, v43, v43
	v_mul_f32_e32 v156, v45, v45
	v_mul_f32_e32 v158, v8, v8
	v_mul_f32_e32 v159, v9, v9
	v_pk_fma_f32 v[148:149], v[42:43], v[42:43], v[148:149] op_sel_hi:[1,1,0]
	v_pk_fma_f32 v[156:157], v[44:45], v[44:45], v[156:157] op_sel_hi:[1,1,0]
	v_mov_b32_e32 v149, v158
	v_mov_b32_e32 v157, v159
	v_pk_add_f32 v[148:149], v[148:149], v[156:157]
	s_add_u32 s24, s6, 0x2800
	v_pk_add_f32 v[146:147], v[146:147], v[148:149]
	v_mul_f32_e32 v148, v113, v113
	v_add_f32_e32 v146, v146, v147
	v_mul_f32_e32 v147, v111, v111
	v_fmac_f32_e32 v147, v110, v110
	v_fmac_f32_e32 v148, v112, v112
	v_add_f32_e32 v147, v147, v148
	v_mul_f32_e32 v148, v75, v75
	v_mul_f32_e32 v149, v77, v77
	v_fmac_f32_e32 v148, v74, v74
	v_fmac_f32_e32 v149, v76, v76
	v_add_f32_e32 v148, v148, v149
	v_add_f32_e32 v147, v147, v148
	v_mul_f32_e32 v148, v3, v3
	v_mul_f32_e32 v149, v5, v5
	v_fmac_f32_e32 v148, v2, v2
	v_fmac_f32_e32 v149, v4, v4
	v_add_f32_e32 v148, v148, v149
	v_add_f32_e32 v147, v147, v148
	v_mul_f32_e32 v148, v11, v11
	v_mul_f32_e32 v149, v13, v13
	v_fmac_f32_e32 v148, v10, v10
	v_fmac_f32_e32 v149, v12, v12
	v_add_f32_e32 v148, v148, v149
	v_mbcnt_lo_u32_b32 v149, -1, 0
	v_mbcnt_hi_u32_b32 v156, -1, v149
	v_and_b32_e32 v149, 64, v156
	v_add_u32_e32 v157, 64, v149
	v_xor_b32_e32 v149, 1, v156
	v_cmp_lt_i32_e32 vcc, v149, v157
	v_add_f32_e32 v147, v147, v148
	s_addc_u32 s25, s7, 0
	v_cndmask_b32_e32 v149, v156, v149, vcc
	v_lshlrev_b32_e32 v149, 2, v149
	ds_bpermute_b32 v158, v149, v153
	ds_bpermute_b32 v159, v149, v160
	ds_bpermute_b32 v166, v149, v161
	ds_bpermute_b32 v167, v149, v162
	s_add_u32 s26, s6, 0x3000
	s_waitcnt lgkmcnt(3)
	v_add_f32_e32 v148, v153, v158
	s_waitcnt lgkmcnt(2)
	v_add_f32_e32 v153, v160, v159
	s_waitcnt lgkmcnt(1)
	v_add_f32_e32 v158, v161, v166
	s_waitcnt lgkmcnt(0)
	v_add_f32_e32 v159, v162, v167
	ds_bpermute_b32 v160, v149, v163
	ds_bpermute_b32 v161, v149, v164
	ds_bpermute_b32 v162, v149, v165
	ds_bpermute_b32 v166, v149, v146
	ds_bpermute_b32 v149, v149, v147
	s_waitcnt lgkmcnt(4)
	v_add_f32_e32 v160, v163, v160
	s_waitcnt lgkmcnt(3)
	v_add_f32_e32 v161, v164, v161
	s_waitcnt lgkmcnt(2)
	v_add_f32_e32 v162, v165, v162
	s_waitcnt lgkmcnt(1)
	v_add_f32_e32 v146, v146, v166
	s_waitcnt lgkmcnt(0)
	v_add_f32_e32 v147, v147, v149
	v_xor_b32_e32 v149, 2, v156
	v_cmp_lt_i32_e32 vcc, v149, v157
	s_addc_u32 s27, s7, 0
	s_add_u32 s28, s6, 0x3800
	v_cndmask_b32_e32 v149, v156, v149, vcc
	v_lshlrev_b32_e32 v149, 2, v149
	ds_bpermute_b32 v163, v149, v148
	ds_bpermute_b32 v164, v149, v153
	ds_bpermute_b32 v165, v149, v158
	ds_bpermute_b32 v166, v149, v159
	ds_bpermute_b32 v167, v149, v160
	s_waitcnt lgkmcnt(4)
; #define GAS __attribute__((address_space(1)))
; __device__ __forceinline__ void rms9_finish(f32x4 (&v)[9][4], bool xe, const float* gain, bf16* o0, bf16* oe, int lane) {
;     ...
;     for (int o = 1; o < 64; o <<= 1) {
; #pragma unroll
;         for (int r = 0; r < 9; ++r) s[r] += __shfl_xor(s[r], o); }
; #pragma unroll
;     for (int r = 0; r < 9; ++r) s[r] = __builtin_amdgcn_rsqf(s[r] * (1.0f / DM) + EPS);
; #pragma unroll
;     for (int j = 0; j < 4; ++j) { const f32x4 g = ((const GAS f32x4*)gain)[lane + 64 * j];
	v_add_f32_e32 v148, v148, v163
	s_waitcnt lgkmcnt(3)
	v_add_f32_e32 v153, v153, v164
	s_waitcnt lgkmcnt(2)
	v_add_f32_e32 v158, v158, v165
	s_waitcnt lgkmcnt(1)
	v_add_f32_e32 v159, v159, v166
	ds_bpermute_b32 v163, v149, v161
	ds_bpermute_b32 v164, v149, v162
	ds_bpermute_b32 v165, v149, v146
	ds_bpermute_b32 v149, v149, v147
	v_xor_b32_e32 v166, 4, v156
	v_cmp_lt_i32_e32 vcc, v166, v157
	s_waitcnt lgkmcnt(4)
	v_add_f32_e32 v160, v160, v167
	s_waitcnt lgkmcnt(3)
	v_add_f32_e32 v161, v161, v163
	v_cndmask_b32_e32 v166, v156, v166, vcc
	v_lshlrev_b32_e32 v166, 2, v166
	ds_bpermute_b32 v167, v166, v148
	s_waitcnt lgkmcnt(3)
	v_add_f32_e32 v162, v162, v164
	s_waitcnt lgkmcnt(2)
	v_add_f32_e32 v146, v146, v165
	s_waitcnt lgkmcnt(1)
	v_add_f32_e32 v147, v147, v149
	ds_bpermute_b32 v149, v166, v153
	ds_bpermute_b32 v163, v166, v158
	ds_bpermute_b32 v164, v166, v159
	ds_bpermute_b32 v165, v166, v160
	s_waitcnt lgkmcnt(4)
	v_add_f32_e32 v148, v148, v167
	ds_bpermute_b32 v167, v166, v161
	s_waitcnt lgkmcnt(4)
	v_add_f32_e32 v149, v153, v149
	s_waitcnt lgkmcnt(3)
	v_add_f32_e32 v153, v158, v163
	s_waitcnt lgkmcnt(2)
	v_add_f32_e32 v158, v159, v164
	s_waitcnt lgkmcnt(1)
	v_add_f32_e32 v159, v160, v165
	v_xor_b32_e32 v165, 8, v156
	v_cmp_lt_i32_e32 vcc, v165, v157
	s_waitcnt lgkmcnt(0)
	v_add_f32_e32 v160, v161, v167
	ds_bpermute_b32 v161, v166, v162
	v_cndmask_b32_e32 v165, v156, v165, vcc
	v_lshlrev_b32_e32 v165, 2, v165
	ds_bpermute_b32 v163, v166, v146
	ds_bpermute_b32 v164, v166, v147
	ds_bpermute_b32 v166, v165, v148
	ds_bpermute_b32 v167, v165, v149
	s_waitcnt lgkmcnt(4)
	v_add_f32_e32 v161, v162, v161
	s_waitcnt lgkmcnt(3)
	v_add_f32_e32 v162, v146, v163
	s_waitcnt lgkmcnt(2)
	v_add_f32_e32 v163, v147, v164
	s_waitcnt lgkmcnt(1)
	v_add_f32_e32 v164, v148, v166
	s_waitcnt lgkmcnt(0)
	v_add_f32_e32 v166, v149, v167
	global_load_dwordx4 v[146:149], v152, s[68:69]
	ds_bpermute_b32 v168, v165, v158
	ds_bpermute_b32 v167, v165, v153
	ds_bpermute_b32 v170, v165, v160
	ds_bpermute_b32 v169, v165, v159
	ds_bpermute_b32 v171, v165, v161
	s_waitcnt lgkmcnt(4)
	v_add_f32_e32 v158, v158, v168
	v_xor_b32_e32 v168, 16, v156
	s_waitcnt lgkmcnt(3)
	v_add_f32_e32 v153, v153, v167
	ds_bpermute_b32 v167, v165, v162
	v_cmp_lt_i32_e32 vcc, v168, v157
	s_waitcnt lgkmcnt(3)
	v_add_f32_e32 v160, v160, v170
	ds_bpermute_b32 v165, v165, v163
	v_cndmask_b32_e32 v168, v156, v168, vcc
	v_lshlrev_b32_e32 v168, 2, v168
	ds_bpermute_b32 v170, v168, v166
	s_waitcnt lgkmcnt(4)
	v_add_f32_e32 v159, v159, v169
	s_waitcnt lgkmcnt(2)
	v_add_f32_e32 v162, v162, v167
	ds_bpermute_b32 v167, v168, v159
	v_add_f32_e32 v161, v161, v171
	ds_bpermute_b32 v169, v168, v164
	ds_bpermute_b32 v171, v168, v153
	s_waitcnt lgkmcnt(4)
	v_add_f32_e32 v163, v163, v165
	s_waitcnt lgkmcnt(3)
	v_add_f32_e32 v165, v166, v170
	ds_bpermute_b32 v166, v168, v158
	s_waitcnt lgkmcnt(3)
	v_add_f32_e32 v159, v159, v167
	v_xor_b32_e32 v167, 32, v156
	v_cmp_lt_i32_e32 vcc, v167, v157
	s_waitcnt lgkmcnt(2)
	v_add_f32_e32 v164, v164, v169
	s_waitcnt lgkmcnt(1)
	v_add_f32_e32 v153, v153, v171
	v_cndmask_b32_e32 v156, v156, v167, vcc
	ds_bpermute_b32 v169, v168, v160
	ds_bpermute_b32 v170, v168, v161
	ds_bpermute_b32 v171, v168, v162
	s_waitcnt lgkmcnt(3)
	v_add_f32_e32 v158, v158, v166
	ds_bpermute_b32 v166, v168, v163
	v_lshlrev_b32_e32 v156, 2, v156
	ds_bpermute_b32 v157, v156, v164
	ds_bpermute_b32 v167, v156, v165
	ds_bpermute_b32 v168, v156, v153
	s_waitcnt lgkmcnt(6)
	v_add_f32_e32 v160, v160, v169
	s_waitcnt lgkmcnt(5)
	v_add_f32_e32 v161, v161, v170
	s_waitcnt lgkmcnt(4)
	v_add_f32_e32 v162, v162, v171
	s_waitcnt lgkmcnt(3)
	v_add_f32_e32 v163, v163, v166
	ds_bpermute_b32 v169, v156, v158
	s_waitcnt lgkmcnt(3)
	v_add_f32_e32 v157, v164, v157
	s_waitcnt lgkmcnt(2)
	v_add_f32_e32 v164, v165, v167
	s_waitcnt lgkmcnt(1)
	v_add_f32_e32 v153, v153, v168
	ds_bpermute_b32 v165, v156, v159
	ds_bpermute_b32 v166, v156, v160
	ds_bpermute_b32 v167, v156, v161
	ds_bpermute_b32 v168, v156, v162
	ds_bpermute_b32 v156, v156, v163
	s_waitcnt lgkmcnt(5)
	v_add_f32_e32 v158, v158, v169
	s_waitcnt lgkmcnt(4)
	v_add_f32_e32 v159, v159, v165
	s_waitcnt lgkmcnt(3)
	v_add_f32_e32 v160, v160, v166
	s_waitcnt lgkmcnt(1)
	v_add_f32_e32 v165, v162, v168
	s_waitcnt lgkmcnt(0)
	v_add_f32_e32 v156, v163, v156
	v_mov_b32_e32 v163, 0x358637bd
	v_fmamk_f32 v153, v153, 0x3a800000, v163
	v_rsq_f32_e32 v168, v153
	v_fmamk_f32 v153, v158, 0x3a800000, v163
	v_fmamk_f32 v157, v157, 0x3a800000, v163
	v_rsq_f32_e32 v166, v153
	v_fmamk_f32 v153, v159, 0x3a800000, v163
	v_add_f32_e32 v161, v161, v167
	v_rsq_f32_e32 v172, v157
	v_fmamk_f32 v157, v164, 0x3a800000, v163
	v_rsq_f32_e32 v164, v153
	v_fmamk_f32 v153, v160, 0x3a800000, v163
	v_rsq_f32_e32 v162, v153
	v_fmamk_f32 v153, v161, 0x3a800000, v163
	v_rsq_f32_e32 v160, v153
	v_fmamk_f32 v153, v165, 0x3a800000, v163
	v_rsq_f32_e32 v170, v157
	v_rsq_f32_e32 v158, v153
	v_mov_b32_e32 v173, v172
	v_pk_mul_f32 v[142:143], v[142:143], v[172:173] op_sel_hi:[1,0]
	v_fmac_f32_e32 v163, 0x3a800000, v156
	v_mov_b32_e32 v171, v170
	s_waitcnt vmcnt(0)
; #define GAS __attribute__((address_space(1)))
; __device__ __forceinline__ unsigned pk2(float lo, float hi) { f32x2_t v = {lo, hi}; bf16x2_t h = __builtin_convertvector(v, bf16x2_t); return __builtin_bit_cast(unsigned, h); }
; __device__ __forceinline__ void rms9_finish(f32x4 (&v)[9][4], bool xe, const float* gain, bf16* o0, bf16* oe, int lane) {
;     ...
; #pragma unroll
;     for (int j = 0; j < 4; ++j) { const f32x4 g = ((const GAS f32x4*)gain)[lane + 64 * j];
; #pragma unroll
;         for (int r = 0; r < 8; ++r) { const float rs = s[r];
;             v2u w; w.x = pk2(v[r][j].x * rs * g.x, v[r][j].y * rs * g.y); w.y = pk2(v[r][j].z * rs * g.z, v[r][j].w * rs * g.w); ((GAS v2u*)(o0 + (size_t)r * DM))[lane + 64 * j] = w; }
;         if (xe) { const float rs = s[8]; v2u w; w.x = pk2(v[8][j].x * rs * g.x, v[8][j].y * rs * g.y); w.y = pk2(v[8][j].z * rs * g.z, v[8][j].w * rs * g.w); ((GAS v2u*)oe)[lane + 64 * j] = w; } }
	v_pk_mul_f32 v[142:143], v[142:143], v[146:147]
	v_mov_b32_e32 v159, v158
	v_rsq_f32_e32 v156, v163
	v_cvt_pk_bf16_f32 v176, v142, v143
	v_pk_mul_f32 v[142:143], v[144:145], v[172:173] op_sel_hi:[1,0]
	v_pk_mul_f32 v[138:139], v[138:139], v[170:171] op_sel_hi:[1,0]
	v_pk_mul_f32 v[140:141], v[140:141], v[170:171] op_sel_hi:[1,0]
	v_mov_b32_e32 v169, v168
	v_mov_b32_e32 v167, v166
	v_mov_b32_e32 v165, v164
	v_mov_b32_e32 v163, v162
	v_mov_b32_e32 v161, v160
	v_pk_mul_f32 v[114:115], v[114:115], v[158:159] op_sel_hi:[1,0]
	v_pk_mul_f32 v[116:117], v[116:117], v[158:159] op_sel_hi:[1,0]
	v_mov_b32_e32 v153, 0
	v_pk_mul_f32 v[142:143], v[142:143], v[148:149]
	v_pk_mul_f32 v[138:139], v[138:139], v[146:147]
	v_pk_mul_f32 v[140:141], v[140:141], v[148:149]
	v_pk_mul_f32 v[134:135], v[134:135], v[168:169] op_sel_hi:[1,0]
	v_pk_mul_f32 v[136:137], v[136:137], v[168:169] op_sel_hi:[1,0]
	v_pk_mul_f32 v[130:131], v[130:131], v[166:167] op_sel_hi:[1,0]
	v_pk_mul_f32 v[132:133], v[132:133], v[166:167] op_sel_hi:[1,0]
	v_pk_mul_f32 v[126:127], v[126:127], v[164:165] op_sel_hi:[1,0]
	v_pk_mul_f32 v[128:129], v[128:129], v[164:165] op_sel_hi:[1,0]
	v_pk_mul_f32 v[122:123], v[122:123], v[162:163] op_sel_hi:[1,0]
	v_pk_mul_f32 v[124:125], v[124:125], v[162:163] op_sel_hi:[1,0]
	v_pk_mul_f32 v[118:119], v[118:119], v[160:161] op_sel_hi:[1,0]
	v_pk_mul_f32 v[120:121], v[120:121], v[160:161] op_sel_hi:[1,0]
	v_pk_mul_f32 v[114:115], v[146:147], v[114:115]
	v_pk_mul_f32 v[116:117], v[148:149], v[116:117]
	v_lshl_add_u64 v[174:175], s[68:69], 0, v[152:153]
	v_cvt_pk_bf16_f32 v177, v142, v143
	v_lshlrev_b32_e32 v152, 3, v154
	v_cvt_pk_bf16_f32 v138, v138, v139
	v_cvt_pk_bf16_f32 v139, v140, v141
	v_pk_mul_f32 v[134:135], v[134:135], v[146:147]
	v_pk_mul_f32 v[136:137], v[136:137], v[148:149]
	v_pk_mul_f32 v[130:131], v[130:131], v[146:147]
	v_pk_mul_f32 v[132:133], v[132:133], v[148:149]
	v_pk_mul_f32 v[126:127], v[146:147], v[126:127]
	v_pk_mul_f32 v[128:129], v[148:149], v[128:129]
	v_pk_mul_f32 v[122:123], v[146:147], v[122:123]
	v_pk_mul_f32 v[124:125], v[148:149], v[124:125]
	v_pk_mul_f32 v[118:119], v[146:147], v[118:119]
	v_pk_mul_f32 v[120:121], v[148:149], v[120:121]
	v_cvt_pk_bf16_f32 v114, v114, v115
	v_cvt_pk_bf16_f32 v115, v116, v117
	v_cndmask_b32_e64 v116, 0, 1, s[20:21]
	s_mov_b32 s36, s34
	v_lshl_add_u64 v[142:143], s[6:7], 0, v[152:153]
	global_store_dwordx2 v152, v[176:177], s[6:7] sc1
	global_store_dwordx2 v152, v[138:139], s[6:7] offset:2048 sc1
	v_cvt_pk_bf16_f32 v134, v134, v135
	v_cvt_pk_bf16_f32 v135, v136, v137
	v_cvt_pk_bf16_f32 v130, v130, v131
	v_cvt_pk_bf16_f32 v131, v132, v133
	v_cvt_pk_bf16_f32 v126, v126, v127
	v_cvt_pk_bf16_f32 v127, v128, v129
	v_cvt_pk_bf16_f32 v122, v122, v123
	v_cvt_pk_bf16_f32 v123, v124, v125
	v_cvt_pk_bf16_f32 v118, v118, v119
	v_cvt_pk_bf16_f32 v119, v120, v121
	s_addc_u32 s29, s7, 0
	v_cmp_ne_u32_e64 s[6:7], 1, v116
	s_andn2_b64 vcc, exec, s[20:21]
	global_store_dwordx2 v152, v[134:135], s[8:9] sc1
	global_store_dwordx2 v152, v[130:131], s[10:11] sc1
	global_store_dwordx2 v152, v[126:127], s[22:23] sc1
	global_store_dwordx2 v152, v[122:123], s[24:25] sc1
	global_store_dwordx2 v152, v[118:119], s[26:27] sc1
	global_store_dwordx2 v152, v[114:115], s[28:29] sc1
	s_cbranch_vccnz .LBB0_34
	v_pk_mul_f32 v[110:111], v[110:111], v[156:157] op_sel_hi:[1,0]
	v_pk_mul_f32 v[112:113], v[112:113], v[156:157] op_sel_hi:[1,0]
	v_pk_mul_f32 v[110:111], v[146:147], v[110:111]
	v_pk_mul_f32 v[112:113], v[148:149], v[112:113]
	v_cvt_pk_bf16_f32 v110, v110, v111
	v_cvt_pk_bf16_f32 v111, v112, v113
	global_store_dwordx2 v152, v[110:111], s[4:5] sc1
.LBB0_34:
	global_load_dwordx4 v[110:113], v[174:175], off offset:1024
	v_pk_mul_f32 v[106:107], v[106:107], v[172:173]
	v_pk_mul_f32 v[108:109], v[108:109], v[172:173]
	v_pk_mul_f32 v[90:91], v[90:91], v[170:171]
	v_pk_mul_f32 v[92:93], v[92:93], v[170:171]
	v_pk_mul_f32 v[82:83], v[82:83], v[168:169]
	v_pk_mul_f32 v[84:85], v[84:85], v[168:169]
	v_pk_mul_f32 v[86:87], v[86:87], v[166:167]
	v_pk_mul_f32 v[88:89], v[88:89], v[166:167]
	v_pk_mul_f32 v[78:79], v[78:79], v[164:165]
	v_pk_mul_f32 v[80:81], v[80:81], v[164:165]
	v_pk_mul_f32 v[102:103], v[102:103], v[162:163]
	v_pk_mul_f32 v[104:105], v[104:105], v[162:163]
	v_pk_mul_f32 v[98:99], v[98:99], v[160:161]
	v_pk_mul_f32 v[100:101], v[100:101], v[160:161]
	v_pk_mul_f32 v[94:95], v[94:95], v[158:159]
	v_pk_mul_f32 v[96:97], v[96:97], v[158:159]
	s_and_b64 vcc, exec, s[6:7]
	v_lshlrev_b32_e32 v114, 3, v150
	s_waitcnt vmcnt(0)
	v_pk_mul_f32 v[106:107], v[106:107], v[110:111]
	v_pk_mul_f32 v[108:109], v[108:109], v[112:113]
	v_pk_mul_f32 v[90:91], v[90:91], v[110:111]
	v_pk_mul_f32 v[92:93], v[92:93], v[112:113]
	v_pk_mul_f32 v[82:83], v[82:83], v[110:111]
	v_pk_mul_f32 v[84:85], v[84:85], v[112:113]
	v_pk_mul_f32 v[86:87], v[86:87], v[110:111]
	v_pk_mul_f32 v[88:89], v[88:89], v[112:113]
	v_pk_mul_f32 v[78:79], v[78:79], v[110:111]
	v_pk_mul_f32 v[80:81], v[80:81], v[112:113]
	v_pk_mul_f32 v[102:103], v[102:103], v[110:111]
	v_pk_mul_f32 v[104:105], v[104:105], v[112:113]
	v_pk_mul_f32 v[98:99], v[98:99], v[110:111]
	v_pk_mul_f32 v[100:101], v[100:101], v[112:113]
	v_pk_mul_f32 v[94:95], v[94:95], v[110:111]
	v_pk_mul_f32 v[96:97], v[96:97], v[112:113]
	v_cvt_pk_bf16_f32 v106, v106, v107
	v_cvt_pk_bf16_f32 v107, v108, v109
	v_cvt_pk_bf16_f32 v90, v90, v91
	v_cvt_pk_bf16_f32 v91, v92, v93
	v_cvt_pk_bf16_f32 v82, v82, v83
	v_cvt_pk_bf16_f32 v83, v84, v85
	v_cvt_pk_bf16_f32 v84, v86, v87
	v_cvt_pk_bf16_f32 v85, v88, v89
	v_cvt_pk_bf16_f32 v78, v78, v79
	v_cvt_pk_bf16_f32 v79, v80, v81
	v_cvt_pk_bf16_f32 v80, v102, v103
	v_cvt_pk_bf16_f32 v81, v104, v105
	v_cvt_pk_bf16_f32 v86, v98, v99
	v_cvt_pk_bf16_f32 v87, v100, v101
	v_cvt_pk_bf16_f32 v88, v94, v95
	v_cvt_pk_bf16_f32 v89, v96, v97
	global_store_dwordx2 v[142:143], v[106:107], off offset:512 sc1
	global_store_dwordx2 v[142:143], v[90:91], off offset:2560 sc1
	global_store_dwordx2 v114, v[82:83], s[8:9] sc1
	global_store_dwordx2 v114, v[84:85], s[10:11] sc1
	global_store_dwordx2 v114, v[78:79], s[22:23] sc1
	global_store_dwordx2 v114, v[80:81], s[24:25] sc1
	global_store_dwordx2 v114, v[86:87], s[26:27] sc1
	global_store_dwordx2 v114, v[88:89], s[28:29] sc1
	s_cbranch_vccnz .LBB0_36
	v_pk_mul_f32 v[74:75], v[74:75], v[156:157] op_sel_hi:[1,0]
	v_pk_mul_f32 v[76:77], v[76:77], v[156:157] op_sel_hi:[1,0]
	v_pk_mul_f32 v[74:75], v[74:75], v[110:111]
	v_pk_mul_f32 v[76:77], v[76:77], v[112:113]
	v_cvt_pk_bf16_f32 v74, v74, v75
	v_cvt_pk_bf16_f32 v75, v76, v77
	global_store_dwordx2 v152, v[74:75], s[4:5] offset:512 sc1
; #define GAS __attribute__((address_space(1)))
; __device__ __forceinline__ unsigned pk2(float lo, float hi) { f32x2_t v = {lo, hi}; bf16x2_t h = __builtin_convertvector(v, bf16x2_t); return __builtin_bit_cast(unsigned, h); }
; __device__ __forceinline__ void rms9_finish(f32x4 (&v)[9][4], bool xe, const float* gain, bf16* o0, bf16* oe, int lane) {
;     ...
; #pragma unroll
;     for (int j = 0; j < 4; ++j) { const f32x4 g = ((const GAS f32x4*)gain)[lane + 64 * j];
; #pragma unroll
;         for (int r = 0; r < 8; ++r) { const float rs = s[r];
;             v2u w; w.x = pk2(v[r][j].x * rs * g.x, v[r][j].y * rs * g.y); w.y = pk2(v[r][j].z * rs * g.z, v[r][j].w * rs * g.w); ((GAS v2u*)(o0 + (size_t)r * DM))[lane + 64 * j] = w; }
;         if (xe) { const float rs = s[8]; v2u w; w.x = pk2(v[8][j].x * rs * g.x, v[8][j].y * rs * g.y); w.y = pk2(v[8][j].z * rs * g.z, v[8][j].w * rs * g.w); ((GAS v2u*)oe)[lane + 64 * j] = w; } }
.LBB0_36:
	global_load_dwordx4 v[74:77], v[174:175], off offset:2048
	v_pk_mul_f32 v[70:71], v[70:71], v[172:173]
	v_pk_mul_f32 v[72:73], v[72:73], v[172:173]
	v_pk_mul_f32 v[66:67], v[66:67], v[170:171]
	v_pk_mul_f32 v[68:69], v[68:69], v[170:171]
	v_pk_mul_f32 v[62:63], v[62:63], v[168:169]
	v_pk_mul_f32 v[64:65], v[64:65], v[168:169]
	v_pk_mul_f32 v[58:59], v[58:59], v[166:167]
	v_pk_mul_f32 v[60:61], v[60:61], v[166:167]
	v_pk_mul_f32 v[54:55], v[54:55], v[164:165]
	v_pk_mul_f32 v[56:57], v[56:57], v[164:165]
	v_pk_mul_f32 v[50:51], v[50:51], v[162:163]
	v_pk_mul_f32 v[52:53], v[52:53], v[162:163]
	v_pk_mul_f32 v[46:47], v[46:47], v[160:161]
	v_pk_mul_f32 v[48:49], v[48:49], v[160:161]
	v_pk_mul_f32 v[42:43], v[42:43], v[158:159]
	v_pk_mul_f32 v[44:45], v[44:45], v[158:159]
	s_and_b64 vcc, exec, s[6:7]
	s_mov_b32 s34, s36
	v_lshlrev_b32_e32 v78, 3, v155
	s_waitcnt vmcnt(0)
	v_pk_mul_f32 v[70:71], v[70:71], v[74:75]
	v_pk_mul_f32 v[72:73], v[72:73], v[76:77]
	v_pk_mul_f32 v[66:67], v[66:67], v[74:75]
	v_pk_mul_f32 v[68:69], v[68:69], v[76:77]
	v_pk_mul_f32 v[62:63], v[62:63], v[74:75]
	v_pk_mul_f32 v[64:65], v[64:65], v[76:77]
	v_pk_mul_f32 v[58:59], v[58:59], v[74:75]
	v_pk_mul_f32 v[60:61], v[60:61], v[76:77]
	v_pk_mul_f32 v[54:55], v[54:55], v[74:75]
	v_pk_mul_f32 v[56:57], v[56:57], v[76:77]
	v_pk_mul_f32 v[50:51], v[50:51], v[74:75]
	v_pk_mul_f32 v[52:53], v[52:53], v[76:77]
	v_pk_mul_f32 v[46:47], v[46:47], v[74:75]
	v_pk_mul_f32 v[48:49], v[48:49], v[76:77]
	v_pk_mul_f32 v[42:43], v[42:43], v[74:75]
	v_pk_mul_f32 v[44:45], v[44:45], v[76:77]
	v_cvt_pk_bf16_f32 v70, v70, v71
	v_cvt_pk_bf16_f32 v71, v72, v73
	v_cvt_pk_bf16_f32 v66, v66, v67
	v_cvt_pk_bf16_f32 v67, v68, v69
	v_cvt_pk_bf16_f32 v62, v62, v63
	v_cvt_pk_bf16_f32 v63, v64, v65
	v_cvt_pk_bf16_f32 v58, v58, v59
	v_cvt_pk_bf16_f32 v59, v60, v61
	v_cvt_pk_bf16_f32 v54, v54, v55
	v_cvt_pk_bf16_f32 v55, v56, v57
	v_cvt_pk_bf16_f32 v50, v50, v51
	v_cvt_pk_bf16_f32 v51, v52, v53
	v_cvt_pk_bf16_f32 v46, v46, v47
	v_cvt_pk_bf16_f32 v47, v48, v49
	v_cvt_pk_bf16_f32 v42, v42, v43
	v_cvt_pk_bf16_f32 v43, v44, v45
	global_store_dwordx2 v[142:143], v[70:71], off offset:1024 sc1
	global_store_dwordx2 v[142:143], v[66:67], off offset:3072 sc1
	global_store_dwordx2 v78, v[62:63], s[8:9] sc1
	global_store_dwordx2 v78, v[58:59], s[10:11] sc1
	global_store_dwordx2 v78, v[54:55], s[22:23] sc1
	global_store_dwordx2 v78, v[50:51], s[24:25] sc1
	global_store_dwordx2 v78, v[46:47], s[26:27] sc1
	global_store_dwordx2 v78, v[42:43], s[28:29] sc1
	s_cbranch_vccnz .LBB0_38
	v_pk_mul_f32 v[2:3], v[2:3], v[156:157] op_sel_hi:[1,0]
	v_pk_mul_f32 v[4:5], v[4:5], v[156:157] op_sel_hi:[1,0]
	v_pk_mul_f32 v[2:3], v[2:3], v[74:75]
	v_pk_mul_f32 v[4:5], v[4:5], v[76:77]
	v_cvt_pk_bf16_f32 v2, v2, v3
	v_cvt_pk_bf16_f32 v3, v4, v5
	global_store_dwordx2 v152, v[2:3], s[4:5] offset:1024 sc1
.LBB0_38:
	global_load_dwordx4 v[2:5], v[174:175], off offset:3072
	v_pk_mul_f32 v[38:39], v[38:39], v[172:173]
	v_pk_mul_f32 v[40:41], v[40:41], v[172:173]
	v_pk_mul_f32 v[34:35], v[34:35], v[170:171]
	v_pk_mul_f32 v[36:37], v[36:37], v[170:171]
	v_pk_mul_f32 v[30:31], v[30:31], v[168:169]
	v_pk_mul_f32 v[32:33], v[32:33], v[168:169]
	v_pk_mul_f32 v[26:27], v[26:27], v[166:167]
	v_pk_mul_f32 v[28:29], v[28:29], v[166:167]
	v_pk_mul_f32 v[22:23], v[22:23], v[164:165]
	v_pk_mul_f32 v[24:25], v[24:25], v[164:165]
	v_pk_mul_f32 v[18:19], v[18:19], v[162:163]
	v_pk_mul_f32 v[20:21], v[20:21], v[162:163]
	v_pk_mul_f32 v[14:15], v[14:15], v[160:161]
	v_pk_mul_f32 v[16:17], v[16:17], v[160:161]
	v_pk_mul_f32 v[6:7], v[6:7], v[158:159]
	v_pk_mul_f32 v[8:9], v[8:9], v[158:159]
	s_and_b64 vcc, exec, s[6:7]
	v_lshlrev_b32_e32 v42, 3, v151
	s_waitcnt vmcnt(0)
	v_pk_mul_f32 v[38:39], v[38:39], v[2:3]
	v_pk_mul_f32 v[40:41], v[40:41], v[4:5]
	v_pk_mul_f32 v[34:35], v[34:35], v[2:3]
	v_pk_mul_f32 v[36:37], v[36:37], v[4:5]
	v_pk_mul_f32 v[30:31], v[30:31], v[2:3]
	v_pk_mul_f32 v[32:33], v[32:33], v[4:5]
	v_pk_mul_f32 v[26:27], v[26:27], v[2:3]
	v_pk_mul_f32 v[28:29], v[28:29], v[4:5]
	v_pk_mul_f32 v[22:23], v[22:23], v[2:3]
	v_pk_mul_f32 v[24:25], v[24:25], v[4:5]
	v_pk_mul_f32 v[18:19], v[18:19], v[2:3]
	v_pk_mul_f32 v[20:21], v[20:21], v[4:5]
	v_pk_mul_f32 v[14:15], v[14:15], v[2:3]
	v_pk_mul_f32 v[16:17], v[16:17], v[4:5]
	v_pk_mul_f32 v[6:7], v[6:7], v[2:3]
	v_pk_mul_f32 v[8:9], v[8:9], v[4:5]
	v_cvt_pk_bf16_f32 v38, v38, v39
	v_cvt_pk_bf16_f32 v39, v40, v41
	v_cvt_pk_bf16_f32 v34, v34, v35
	v_cvt_pk_bf16_f32 v35, v36, v37
	v_cvt_pk_bf16_f32 v30, v30, v31
	v_cvt_pk_bf16_f32 v31, v32, v33
	v_cvt_pk_bf16_f32 v26, v26, v27
	v_cvt_pk_bf16_f32 v27, v28, v29
	v_cvt_pk_bf16_f32 v22, v22, v23
	v_cvt_pk_bf16_f32 v23, v24, v25
	v_cvt_pk_bf16_f32 v18, v18, v19
	v_cvt_pk_bf16_f32 v19, v20, v21
	v_cvt_pk_bf16_f32 v14, v14, v15
	v_cvt_pk_bf16_f32 v15, v16, v17
	v_cvt_pk_bf16_f32 v6, v6, v7
	v_cvt_pk_bf16_f32 v7, v8, v9
	global_store_dwordx2 v[142:143], v[38:39], off offset:1536 sc1
	global_store_dwordx2 v[142:143], v[34:35], off offset:3584 sc1
	global_store_dwordx2 v42, v[30:31], s[8:9] sc1
	global_store_dwordx2 v42, v[26:27], s[10:11] sc1
	global_store_dwordx2 v42, v[22:23], s[22:23] sc1
	global_store_dwordx2 v42, v[18:19], s[24:25] sc1
	global_store_dwordx2 v42, v[14:15], s[26:27] sc1
	global_store_dwordx2 v42, v[6:7], s[28:29] sc1
	s_cbranch_vccnz .LBB0_40
	v_pk_mul_f32 v[6:7], v[10:11], v[156:157] op_sel_hi:[1,0]
	s_nop 0
	v_pk_mul_f32 v[2:3], v[6:7], v[2:3]
	v_pk_mul_f32 v[6:7], v[12:13], v[156:157] op_sel_hi:[1,0]
	v_cvt_pk_bf16_f32 v2, v2, v3
	v_pk_mul_f32 v[4:5], v[6:7], v[4:5]
	s_nop 0
	v_cvt_pk_bf16_f32 v3, v4, v5
	global_store_dwordx2 v152, v[2:3], s[4:5] offset:1536 sc1
